# short-conv items distributed over all 256 workgroups (stride 2048) instead of workgroups 64..255
# baseline (speedup 1.0000x reference)
; __global__ void __launch_bounds__(512, 2) mk_fwd(Args args) {
;     ...
;             if (G == 256) {
;                 if (vcu >= 128) attn_sample_unit(args, l, vcu - 128, lds, tid);
;     ...
;                 if (vcu >= 64) for (int it = (vcu - 64) * 8 + wave; it < (MT / 8) * 2; it += 192 * 8) sconv_item(args, l, it, lane);
;     ...
;             } else {
;                 for (int u = vcu; u < 128; u += G) attn_sample_unit(args, l, u, lds, tid);
;     ...
;                 for (int it = gw; it < (MT / 8) * 2; it += ngw) sconv_item(args, l, it, lane);
.LBB0_658:
	v_readlane_b32 s2, v254, 49
	v_readlane_b32 s3, v254, 42
	v_readlane_b32 s14, v254, 47
	s_nop 1
	s_add_i32 s2, s2, 0x800
	s_add_i32 s3, s3, 0x40000
	s_add_i32 s14, s14, 0x200
	s_branch .LBB0_686

; __global__ void __launch_bounds__(512, 2) mk_fwd(Args args) {
;     ...
;                 if (vcu >= 64) for (int it = (vcu - 64) * 8 + wave; it < (MT / 8) * 2; it += 192 * 8) sconv_item(args, l, it, lane);
;     ...
;             } else {
;                 for (int u = vcu; u < 128; u += G) attn_sample_unit(args, l, u, lds, tid);
;     ...
;                 for (int it = gw; it < (MT / 8) * 2; it += ngw) sconv_item(args, l, it, lane);
.LBB0_685:
	s_addk_i32 s14, 0x800
	s_add_i32 s3, s3, 0x100000
	s_addk_i32 s2, 0x2000
	s_cmpk_gt_i32 s14, 0xaff
	s_mov_b32 s24, 0x10000
	s_cbranch_scc1 .LBB0_659
